# P0: LRU gate-weight bf16 conversion with both layers' loads in flight (pointer select by scalar loads)
# speedup vs baseline: 1.0006x; 1.0006x over previous
.LBB0_593:
	s_or_b64 exec, exec, s[4:5]
	s_mov_b32 s3, 0x40000
	v_cmp_gt_i32_e32 vcc, s3, v2
	s_and_saveexec_b64 s[4:5], vcc
	s_cbranch_execz .LBB0_596
	s_load_dwordx2 s[6:7], s[0:1], 0xc8
	s_load_dwordx2 s[8:9], s[0:1], 0x58
	s_load_dwordx2 s[10:11], s[0:1], 0x68
	v_readlane_b32 s3, v254, 44
	v_lshrrev_b32_e32 v0, 13, v2
	v_and_b32_e32 v0, 8, v0
	v_bfe_u32 v6, v2, 12, 3
	v_or_b32_e32 v0, v0, v6
	v_lshlrev_b32_e32 v0, 14, v0
	v_lshl_add_u32 v6, v56, 6, s3
	v_and_b32_e32 v6, 0xfc0, v6
	v_lshl_add_u32 v0, v6, 2, v0
	v_lshrrev_b32_e32 v6, 4, v2
	v_and_b32_e32 v6, 0xfc, v6
	v_add_u32_e32 v0, v0, v6
	v_and_b32_e32 v6, 0x8000, v2
	v_cmp_eq_u32_e32 vcc, 0, v6
	s_waitcnt lgkmcnt(0)
	v_lshl_add_u64 v[4:5], v[2:3], 1, s[6:7]
	s_mov_b64 s[6:7], 0x300000
	v_lshl_add_u64 v[4:5], v[4:5], 0, s[6:7]
	v_mov_b32_e32 v8, s10
	v_mov_b32_e32 v9, s11
	v_mov_b32_e32 v10, s8
	v_mov_b32_e32 v11, s9
	v_cndmask_b32_e32 v8, v8, v10, vcc
	v_cndmask_b32_e32 v9, v9, v11, vcc
	v_lshl_add_u64 v[8:9], v[8:9], 0, v[0:1]
	v_lshl_add_u64 v[12:13], v[8:9], 0, s[66:67]
	global_load_dword v10, v[8:9], off
	global_load_dword v11, v[12:13], off
	v_lshl_add_u64 v[6:7], v[4:5], 0, s[66:67]
	v_add_u32_e32 v2, 0x40000, v2
	s_waitcnt vmcnt(0)
	v_cvt_pk_bf16_f32 v10, v10, v10
	v_cvt_pk_bf16_f32 v11, v11, v11
	global_store_short v[4:5], v10, off
	global_store_short v[6:7], v11, off
